# merge sigmoid uses v_rcp_f32 (as the baseline LRU gates do) instead of the IEEE division expansion; post-QK s_nop window filled with loop-tail pointer increments and ones moves
# speedup vs baseline: 1.0333x; 1.0066x over previous
; DI float sigmoidf_(float x) { return 1.f / (1.f + __expf(-x)); }
; DI void phase_merge(const Params& P, int layer, char* smem) {
;     ...
;       gemm_main<64>(G, dG, dP, R, k > 0, smem);
; #pragma unroll
;       for (int mi = 0; mi < 2; ++mi)
; #pragma unroll
;         for (int i = 0; i < 16; ++i) G[mi][0][i] = sigmoidf_(G[mi][0][i]);
;       f32x16 Pk[2][1];
;       zero_acc<1>(Pk);
;       gemm_main<64>(Pk, dP, dN, R, true, smem);
; #pragma unroll
;       for (int mi = 0; mi < 2; ++mi)
; #pragma unroll
;         for (int i = 0; i < 16; ++i) M[mi][0][i] += Pk[mi][0][i] * G[mi][0][i];
.LBB0_105:
	v_mul_f32_e32 v48, 0xbfb8aa3b, v48
	v_exp_f32_e32 v120, v48
	v_mul_f32_e32 v48, 0xbfb8aa3b, v49
	v_exp_f32_e32 v121, v48
	v_mul_f32_e32 v48, 0xbfb8aa3b, v50
	v_exp_f32_e32 v122, v48
	v_mul_f32_e32 v48, 0xbfb8aa3b, v51
	v_exp_f32_e32 v123, v48
	v_mul_f32_e32 v48, 0xbfb8aa3b, v52
	v_exp_f32_e32 v158, v48
	v_mul_f32_e32 v48, 0xbfb8aa3b, v53
	v_exp_f32_e32 v159, v48
	v_mul_f32_e32 v48, 0xbfb8aa3b, v54
	v_exp_f32_e32 v116, v48
	v_mul_f32_e32 v48, 0xbfb8aa3b, v55
	v_exp_f32_e32 v117, v48
	v_mul_f32_e32 v48, 0xbfb8aa3b, v56
	v_exp_f32_e32 v114, v48
	v_mul_f32_e32 v48, 0xbfb8aa3b, v57
	v_exp_f32_e32 v115, v48
	v_mul_f32_e32 v48, 0xbfb8aa3b, v58
	v_exp_f32_e32 v112, v48
	v_mul_f32_e32 v48, 0xbfb8aa3b, v59
	v_exp_f32_e32 v113, v48
	v_mul_f32_e32 v48, 0xbfb8aa3b, v60
	v_exp_f32_e32 v54, v48
	v_mul_f32_e32 v48, 0xbfb8aa3b, v61
	v_mul_f32_e32 v32, 0xbfb8aa3b, v32
	v_exp_f32_e32 v55, v48
	v_mul_f32_e32 v48, 0xbfb8aa3b, v62
	v_exp_f32_e32 v62, v32
	v_mul_f32_e32 v32, 0xbfb8aa3b, v33
	v_exp_f32_e32 v58, v48
	v_mul_f32_e32 v48, 0xbfb8aa3b, v63
	v_exp_f32_e32 v63, v32
	v_mul_f32_e32 v32, 0xbfb8aa3b, v34
	v_exp_f32_e32 v60, v32
	v_mul_f32_e32 v32, 0xbfb8aa3b, v35
	v_exp_f32_e32 v61, v32
	v_mul_f32_e32 v32, 0xbfb8aa3b, v36
	v_exp_f32_e32 v56, v32
	v_mul_f32_e32 v32, 0xbfb8aa3b, v37
	v_exp_f32_e32 v57, v32
	v_mul_f32_e32 v32, 0xbfb8aa3b, v38
	v_exp_f32_e32 v52, v32
	v_mul_f32_e32 v32, 0xbfb8aa3b, v39
	v_exp_f32_e32 v53, v32
	v_mul_f32_e32 v32, 0xbfb8aa3b, v40
	v_exp_f32_e32 v50, v32
	v_mul_f32_e32 v32, 0xbfb8aa3b, v41
	v_exp_f32_e32 v51, v32
	v_mul_f32_e32 v32, 0xbfb8aa3b, v42
	v_exp_f32_e32 v59, v48
	v_exp_f32_e32 v48, v32
	v_mul_f32_e32 v32, 0xbfb8aa3b, v43
	v_exp_f32_e32 v49, v32
	v_mul_f32_e32 v32, 0xbfb8aa3b, v44
	v_exp_f32_e32 v40, v32
	v_mul_f32_e32 v32, 0xbfb8aa3b, v45
	v_exp_f32_e32 v41, v32
	v_mul_f32_e32 v32, 0xbfb8aa3b, v46
	v_exp_f32_e32 v36, v32
	v_mul_f32_e32 v32, 0xbfb8aa3b, v47
	v_exp_f32_e32 v37, v32
	v_pk_add_f32 v[32:33], v[120:121], 1.0 op_sel_hi:[1,0]
	v_pk_add_f32 v[54:55], v[54:55], 1.0 op_sel_hi:[1,0]
	v_pk_add_f32 v[58:59], v[58:59], 1.0 op_sel_hi:[1,0]
	v_pk_add_f32 v[62:63], v[62:63], 1.0 op_sel_hi:[1,0]
	v_pk_add_f32 v[60:61], v[60:61], 1.0 op_sel_hi:[1,0]
	v_rcp_f32_e32 v33, v33
	v_pk_add_f32 v[56:57], v[56:57], 1.0 op_sel_hi:[1,0]
	v_pk_add_f32 v[52:53], v[52:53], 1.0 op_sel_hi:[1,0]
	v_pk_add_f32 v[50:51], v[50:51], 1.0 op_sel_hi:[1,0]
	v_rcp_f32_e32 v32, v32
	v_pk_add_f32 v[34:35], v[122:123], 1.0 op_sel_hi:[1,0]
	v_pk_add_f32 v[48:49], v[48:49], 1.0 op_sel_hi:[1,0]
	v_pk_add_f32 v[40:41], v[40:41], 1.0 op_sel_hi:[1,0]
	v_pk_add_f32 v[36:37], v[36:37], 1.0 op_sel_hi:[1,0]
	v_rcp_f32_e32 v35, v35
	v_rcp_f32_e32 v34, v34
	v_pk_add_f32 v[38:39], v[158:159], 1.0 op_sel_hi:[1,0]
	s_nop 0
	v_rcp_f32_e32 v39, v39
	v_rcp_f32_e32 v38, v38
	v_pk_add_f32 v[42:43], v[116:117], 1.0 op_sel_hi:[1,0]
	s_nop 0
	v_rcp_f32_e32 v43, v43
	v_rcp_f32_e32 v42, v42
	v_pk_add_f32 v[44:45], v[114:115], 1.0 op_sel_hi:[1,0]
	s_nop 0
	v_rcp_f32_e32 v45, v45
	v_rcp_f32_e32 v44, v44
	v_pk_add_f32 v[46:47], v[112:113], 1.0 op_sel_hi:[1,0]
	s_nop 0
	v_rcp_f32_e32 v47, v47
	v_rcp_f32_e32 v46, v46
	v_rcp_f32_e32 v55, v55
	v_rcp_f32_e32 v54, v54
	v_rcp_f32_e32 v59, v59
	v_rcp_f32_e32 v58, v58
	v_rcp_f32_e32 v63, v63
	v_rcp_f32_e32 v62, v62
	v_rcp_f32_e32 v61, v61
	v_rcp_f32_e32 v60, v60
	v_rcp_f32_e32 v57, v57
	v_rcp_f32_e32 v56, v56
	v_rcp_f32_e32 v53, v53
	v_rcp_f32_e32 v52, v52
	v_rcp_f32_e32 v51, v51
	v_rcp_f32_e32 v50, v50
	v_rcp_f32_e32 v49, v49
	v_rcp_f32_e32 v48, v48
	v_rcp_f32_e32 v41, v41
	v_rcp_f32_e32 v40, v40
	v_rcp_f32_e32 v37, v37
	v_rcp_f32_e32 v36, v36
	s_setprio 1
	ds_read_b128 v[112:115], v157 offset:4608
	ds_read_b128 v[120:123], v157
	ds_read_b128 v[158:161], v157 offset:32
	ds_read_b128 v[162:165], v118 offset:18432
	ds_read_b128 v[174:177], v118 offset:18464
	s_waitcnt lgkmcnt(1)
	v_mfma_f32_32x32x16_bf16 v[16:31], v[120:123], v[162:165], v[16:31]
	ds_read_b128 v[120:123], v157 offset:4672
	v_mfma_f32_32x32x16_bf16 v[0:15], v[112:115], v[162:165], v[0:15]
	ds_read_b128 v[112:115], v157 offset:4640
	s_waitcnt lgkmcnt(2)
	v_mfma_f32_32x32x16_bf16 v[16:31], v[158:161], v[174:177], v[16:31]
	ds_read_b128 v[158:161], v118 offset:18496
	ds_read_b128 v[116:119], v118 offset:18528
	s_waitcnt lgkmcnt(2)
	v_mfma_f32_32x32x16_bf16 v[0:15], v[112:115], v[174:177], v[0:15]
	s_waitcnt lgkmcnt(1)
	v_mfma_f32_32x32x16_bf16 v[0:15], v[120:123], v[158:161], v[0:15]
	ds_read_b128 v[120:123], v157 offset:4704
	s_waitcnt lgkmcnt(0)
	v_mfma_f32_32x32x16_bf16 v[0:15], v[120:123], v[116:119], v[0:15]
	ds_read_b128 v[112:115], v157 offset:64
	s_waitcnt lgkmcnt(0)
	v_mfma_f32_32x32x16_bf16 v[16:31], v[112:115], v[158:161], v[16:31]
	ds_read_b128 v[112:115], v157 offset:96
	s_waitcnt lgkmcnt(0)
	v_mfma_f32_32x32x16_bf16 v[16:31], v[112:115], v[116:119], v[16:31]
	s_setprio 0
	s_add_u32 s12, s12, 0x200000
	s_addc_u32 s13, s13, 0
	s_add_u32 s10, s10, 0x200000
	s_addc_u32 s11, s11, 0
	s_add_u32 s8, s8, 0x200000
	s_addc_u32 s9, s9, 0
	s_add_u32 s6, s6, 0x200000
	s_addc_u32 s7, s7, 0
	s_nop 2
	v_pk_fma_f32 v[154:155], v[32:33], v[16:17], v[154:155]
	v_pk_fma_f32 v[152:153], v[34:35], v[18:19], v[152:153]
	v_pk_fma_f32 v[150:151], v[38:39], v[20:21], v[150:151]
	v_pk_fma_f32 v[148:149], v[42:43], v[22:23], v[148:149]
	v_pk_fma_f32 v[146:147], v[44:45], v[24:25], v[146:147]
	v_pk_fma_f32 v[144:145], v[46:47], v[26:27], v[144:145]
	v_pk_fma_f32 v[142:143], v[54:55], v[28:29], v[142:143]
	v_pk_fma_f32 v[140:141], v[58:59], v[30:31], v[140:141]
	v_pk_fma_f32 v[138:139], v[62:63], v[0:1], v[138:139]
	v_pk_fma_f32 v[136:137], v[60:61], v[2:3], v[136:137]
	v_pk_fma_f32 v[134:135], v[56:57], v[4:5], v[134:135]
	v_pk_fma_f32 v[132:133], v[52:53], v[6:7], v[132:133]
	v_pk_fma_f32 v[130:131], v[50:51], v[8:9], v[130:131]
	v_pk_fma_f32 v[128:129], v[48:49], v[10:11], v[128:129]
	v_pk_fma_f32 v[126:127], v[40:41], v[12:13], v[126:127]
	s_cmp_eq_u32 s4, 4
	v_pk_fma_f32 v[124:125], v[36:37], v[14:15], v[124:125]
	s_cbranch_scc0 .LBB0_88
; DI void phase_merge(const Params& P, int layer, char* smem) {
;     ...
;     int col = n0 + wn * 32 + r;
; #pragma unroll
;     for (int mi = 0; mi < 2; ++mi)
; #pragma unroll
;       for (int g = 0; g < 4; ++g) {
;         int rl = wm * 64 + mi * 32 + 8 * g + 4 * h;
;         st_rm(MG, 1024, m0 + rl, col, M[mi][0][4 * g], M[mi][0][4 * g + 1], M[mi][0][4 * g + 2], M[mi][0][4 * g + 3]);
;       }
	v_or_b32_e32 v0, s26, v173
	v_add_u32_e32 v2, s25, v180
	v_readlane_b32 s6, v251, 10
	v_ashrrev_i32_e32 v1, 31, v0
	v_readlane_b32 s7, v251, 11
	v_ashrrev_i32_e32 v3, 31, v2
	v_lshlrev_b64 v[4:5], 11, v[2:3]
	v_lshl_add_u64 v[0:1], v[0:1], 1, s[6:7]
	v_lshl_add_u64 v[4:5], v[0:1], 0, v[4:5]
	v_cvt_pk_bf16_f32 v3, v154, s0
	global_store_short v[4:5], v3, off
	v_cvt_pk_bf16_f32 v3, v155, s0
	s_movk_i32 s4, 0x1000
	global_store_short v[4:5], v3, off offset:2048
	v_add_co_u32_e32 v4, vcc, s4, v4
	v_cvt_pk_bf16_f32 v3, v152, s0
	s_nop 0
	v_addc_co_u32_e32 v5, vcc, 0, v5, vcc
	global_store_short v[4:5], v3, off
	v_cvt_pk_bf16_f32 v3, v153, s0
	global_store_short v[4:5], v3, off offset:2048
	v_or_b32_e32 v4, 8, v2
	v_ashrrev_i32_e32 v5, 31, v4
	v_lshlrev_b64 v[4:5], 11, v[4:5]
	v_lshl_add_u64 v[4:5], v[0:1], 0, v[4:5]
	v_cvt_pk_bf16_f32 v3, v150, s0
	global_store_short v[4:5], v3, off
	v_cvt_pk_bf16_f32 v3, v151, s0
	global_store_short v[4:5], v3, off offset:2048
	v_add_co_u32_e32 v4, vcc, s4, v4
	v_cvt_pk_bf16_f32 v3, v148, s0
	s_nop 0
	v_addc_co_u32_e32 v5, vcc, 0, v5, vcc
	global_store_short v[4:5], v3, off
	v_cvt_pk_bf16_f32 v3, v149, s0
	global_store_short v[4:5], v3, off offset:2048
	v_or_b32_e32 v4, 16, v2
	v_ashrrev_i32_e32 v5, 31, v4
	v_lshlrev_b64 v[4:5], 11, v[4:5]
	v_lshl_add_u64 v[4:5], v[0:1], 0, v[4:5]
	v_cvt_pk_bf16_f32 v3, v146, s0
	global_store_short v[4:5], v3, off
	v_cvt_pk_bf16_f32 v3, v147, s0
	global_store_short v[4:5], v3, off offset:2048
	v_add_co_u32_e32 v4, vcc, s4, v4
	v_cvt_pk_bf16_f32 v3, v144, s0
	s_nop 0
	v_addc_co_u32_e32 v5, vcc, 0, v5, vcc
	global_store_short v[4:5], v3, off
	v_cvt_pk_bf16_f32 v3, v145, s0
	global_store_short v[4:5], v3, off offset:2048
	v_or_b32_e32 v4, 24, v2
	v_ashrrev_i32_e32 v5, 31, v4
	v_lshlrev_b64 v[4:5], 11, v[4:5]
	v_lshl_add_u64 v[4:5], v[0:1], 0, v[4:5]
	v_cvt_pk_bf16_f32 v3, v142, s0
	global_store_short v[4:5], v3, off
	v_cvt_pk_bf16_f32 v3, v143, s0
	global_store_short v[4:5], v3, off offset:2048
	v_add_co_u32_e32 v4, vcc, s4, v4
	v_cvt_pk_bf16_f32 v3, v140, s0
	s_nop 0
	v_addc_co_u32_e32 v5, vcc, 0, v5, vcc
	global_store_short v[4:5], v3, off
	v_cvt_pk_bf16_f32 v3, v141, s0
	global_store_short v[4:5], v3, off offset:2048
	v_or_b32_e32 v4, 32, v2
	v_ashrrev_i32_e32 v5, 31, v4
	v_lshlrev_b64 v[4:5], 11, v[4:5]
	v_lshl_add_u64 v[4:5], v[0:1], 0, v[4:5]
	v_cvt_pk_bf16_f32 v3, v138, s0
	global_store_short v[4:5], v3, off
	v_cvt_pk_bf16_f32 v3, v139, s0
	global_store_short v[4:5], v3, off offset:2048
	v_add_co_u32_e32 v4, vcc, s4, v4
	v_cvt_pk_bf16_f32 v3, v136, s0
	s_nop 0
	v_addc_co_u32_e32 v5, vcc, 0, v5, vcc
	global_store_short v[4:5], v3, off
	v_cvt_pk_bf16_f32 v3, v137, s0
	global_store_short v[4:5], v3, off offset:2048
	v_or_b32_e32 v4, 40, v2
	v_ashrrev_i32_e32 v5, 31, v4
	v_lshlrev_b64 v[4:5], 11, v[4:5]
	v_lshl_add_u64 v[4:5], v[0:1], 0, v[4:5]
	v_cvt_pk_bf16_f32 v3, v134, s0
	global_store_short v[4:5], v3, off
	v_cvt_pk_bf16_f32 v3, v135, s0
	global_store_short v[4:5], v3, off offset:2048
	v_add_co_u32_e32 v4, vcc, s4, v4
	v_cvt_pk_bf16_f32 v3, v132, s0
	s_nop 0
	v_addc_co_u32_e32 v5, vcc, 0, v5, vcc
	global_store_short v[4:5], v3, off
	v_cvt_pk_bf16_f32 v3, v133, s0
	global_store_short v[4:5], v3, off offset:2048
	v_or_b32_e32 v4, 48, v2
	v_ashrrev_i32_e32 v5, 31, v4
	v_lshlrev_b64 v[4:5], 11, v[4:5]
	v_lshl_add_u64 v[4:5], v[0:1], 0, v[4:5]
	v_cvt_pk_bf16_f32 v3, v130, s0
	global_store_short v[4:5], v3, off
	v_cvt_pk_bf16_f32 v3, v131, s0
	global_store_short v[4:5], v3, off offset:2048
	v_add_co_u32_e32 v4, vcc, s4, v4
	v_cvt_pk_bf16_f32 v3, v128, s0
	s_nop 0
	v_addc_co_u32_e32 v5, vcc, 0, v5, vcc
	global_store_short v[4:5], v3, off
	v_cvt_pk_bf16_f32 v3, v129, s0
	v_or_b32_e32 v2, 56, v2
	global_store_short v[4:5], v3, off offset:2048
	v_ashrrev_i32_e32 v3, 31, v2
	v_lshlrev_b64 v[2:3], 11, v[2:3]
	v_lshl_add_u64 v[0:1], v[0:1], 0, v[2:3]
	v_cvt_pk_bf16_f32 v2, v126, s0
	global_store_short v[0:1], v2, off
	v_cvt_pk_bf16_f32 v2, v127, s0
	global_store_short v[0:1], v2, off offset:2048
	v_add_co_u32_e32 v0, vcc, 0x1000, v0
	v_readlane_b32 s6, v253, 53
	v_cvt_pk_bf16_f32 v2, v124, s0
	v_addc_co_u32_e32 v1, vcc, 0, v1, vcc
	s_add_i32 s24, s24, s6
	v_readlane_b32 s4, v254, 49
	global_store_short v[0:1], v2, off
	v_cvt_pk_bf16_f32 v2, v125, s0
	s_cmp_ge_i32 s24, s4
	v_readlane_b32 s7, v253, 54
	global_store_short v[0:1], v2, off offset:2048
	s_cbranch_scc0 .LBB0_85

; #define MFMA32(a, b, c) __builtin_amdgcn_mfma_f32_32x32x16_bf16((a), (b), (c), 0, 0, 0)
; DI unsigned pack2(float a, float b) { f32x2_t v = {a, b}; return __builtin_bit_cast(unsigned, __builtin_convertvector(v, bf16x2_t)); }
; template <int DK, int DV>
; DI void attn_map(f32x16 (&O)[DV / 32], float& lsum, const u16* qrow, const u16* K1, int ldk1, const u16* K2, int ldk2, const u16* Vt, int nkeys, char* smem) {
;     ...
;     bf16x8 pf[4];
; #pragma unroll
;     for (int j = 0; j < 2; ++j)
; #pragma unroll
;       for (int st = 0; st < 2; ++st) {
;         u32x4 pk;
;         pk.x = pack2(__builtin_amdgcn_exp2f(s[j][8 * st + 0]), __builtin_amdgcn_exp2f(s[j][8 * st + 1]));
;         pk.y = pack2(__builtin_amdgcn_exp2f(s[j][8 * st + 2]), __builtin_amdgcn_exp2f(s[j][8 * st + 3]));
;         pk.z = pack2(__builtin_amdgcn_exp2f(s[j][8 * st + 4]), __builtin_amdgcn_exp2f(s[j][8 * st + 5]));
;         pk.w = pack2(__builtin_amdgcn_exp2f(s[j][8 * st + 6]), __builtin_amdgcn_exp2f(s[j][8 * st + 7]));
;         pf[j * 2 + st] = __builtin_bit_cast(bf16x8, pk);
;       }
;     __builtin_amdgcn_s_setprio(1);
; #pragma unroll
;     for (int q = 0; q < 4; ++q) lacc = MFMA32(ones, pf[q], lacc);
; #pragma unroll
;     for (int dd = 0; dd < DV / 32; ++dd) {
; #pragma unroll
;       for (int q = 0; q < 4; ++q) {
;         bf16x8 vv = *(const bf16x8*)(Vs + (dd * 32 + r) * VST + q * 16 + 8 * h);
;         O[dd] = MFMA32(vv, pf[q], O[dd]);
;       }
;     }
;     {
;       constexpr int NPV = (DV / 32) * 4;
;       __builtin_amdgcn_sched_group_barrier(0x100, 2, 0);
; #pragma unroll
;       for (int q = 0; q < NPV - 2; ++q) { __builtin_amdgcn_sched_group_barrier(0x008, 1, 0); __builtin_amdgcn_sched_group_barrier(0x100, 1, 0); }
;       __builtin_amdgcn_sched_group_barrier(0x008, 6, 0);
;     }
;     __builtin_amdgcn_s_setprio(0);
.LBB0_381:
	s_add_i32 s10, s10, 64
	v_exp_f32_e32 v96, v96
	v_exp_f32_e32 v97, v97
	v_exp_f32_e32 v98, v98
	v_exp_f32_e32 v99, v99
	v_exp_f32_e32 v100, v100
	v_exp_f32_e32 v101, v101
	v_exp_f32_e32 v102, v102
	v_exp_f32_e32 v103, v103
	v_cvt_pk_bf16_f32 v96, v96, v97
	v_cvt_pk_bf16_f32 v97, v98, v99
	v_cvt_pk_bf16_f32 v98, v100, v101
	v_cvt_pk_bf16_f32 v99, v102, v103
	s_setprio 1
	s_waitcnt lgkmcnt(0)
	v_mfma_f32_32x32x16_bf16 v[48:63], v[200:203], v[96:99], v[48:63]
	ds_read_b128 v[200:203], v168 offset:9280
	v_exp_f32_e32 v100, v104
	v_exp_f32_e32 v101, v105
	v_mfma_f32_32x32x16_bf16 v[32:47], v[204:207], v[96:99], v[32:47]
	ds_read_b128 v[204:207], v168 offset:13888
	v_cvt_pk_bf16_f32 v100, v100, v101
	v_exp_f32_e32 v102, v106
	v_exp_f32_e32 v103, v107
	v_mfma_f32_32x32x16_bf16 v[64:79], v[208:211], v[96:99], v[64:79]
	ds_read_b128 v[208:211], v168 offset:18496
	v_cvt_pk_bf16_f32 v101, v102, v103
	v_exp_f32_e32 v104, v108
	v_exp_f32_e32 v105, v109
	v_exp_f32_e32 v106, v110
	v_mfma_f32_32x32x16_bf16 v[80:95], v[212:215], v[96:99], v[80:95]
	v_exp_f32_e32 v107, v111
	v_cvt_pk_bf16_f32 v102, v104, v105
	v_cvt_pk_bf16_f32 v103, v106, v107
	ds_read_b128 v[212:215], v168 offset:23104
	v_mfma_f32_32x32x16_bf16 v[0:15], v[232:235], v[96:99], v[0:15]
	v_mfma_f32_32x32x16_bf16 v[48:63], v[216:219], v[100:103], v[48:63]
	ds_read_b128 v[216:219], v168 offset:9312
	v_exp_f32_e32 v104, v112
	v_exp_f32_e32 v105, v113
	v_mfma_f32_32x32x16_bf16 v[32:47], v[220:223], v[100:103], v[32:47]
	ds_read_b128 v[220:223], v168 offset:13920
	v_cvt_pk_bf16_f32 v104, v104, v105
	v_exp_f32_e32 v106, v114
	v_exp_f32_e32 v107, v115
	v_mfma_f32_32x32x16_bf16 v[64:79], v[224:227], v[100:103], v[64:79]
	ds_read_b128 v[224:227], v168 offset:18528
	v_cvt_pk_bf16_f32 v105, v106, v107
	v_exp_f32_e32 v108, v116
	v_exp_f32_e32 v109, v117
	v_exp_f32_e32 v110, v118
	v_mfma_f32_32x32x16_bf16 v[80:95], v[228:231], v[100:103], v[80:95]
	v_exp_f32_e32 v111, v119
	v_cvt_pk_bf16_f32 v106, v108, v109
	v_cvt_pk_bf16_f32 v107, v110, v111
	ds_read_b128 v[228:231], v168 offset:23136
	v_mfma_f32_32x32x16_bf16 v[0:15], v[232:235], v[100:103], v[0:15]
	s_waitcnt lgkmcnt(7)
	v_mfma_f32_32x32x16_bf16 v[48:63], v[200:203], v[104:107], v[48:63]
	v_exp_f32_e32 v108, v120
	v_exp_f32_e32 v109, v121
	s_waitcnt lgkmcnt(6)
	v_mfma_f32_32x32x16_bf16 v[32:47], v[204:207], v[104:107], v[32:47]
	v_cvt_pk_bf16_f32 v108, v108, v109
	v_exp_f32_e32 v110, v122
	v_exp_f32_e32 v111, v123
	s_waitcnt lgkmcnt(5)
	v_mfma_f32_32x32x16_bf16 v[64:79], v[208:211], v[104:107], v[64:79]
	v_cvt_pk_bf16_f32 v109, v110, v111
	v_exp_f32_e32 v112, v124
	v_exp_f32_e32 v113, v125
	v_exp_f32_e32 v114, v126
	s_waitcnt lgkmcnt(4)
	v_mfma_f32_32x32x16_bf16 v[80:95], v[212:215], v[104:107], v[80:95]
	v_exp_f32_e32 v115, v127
	v_cvt_pk_bf16_f32 v110, v112, v113
	v_cvt_pk_bf16_f32 v111, v114, v115
	s_nop 0
	v_mfma_f32_32x32x16_bf16 v[0:15], v[232:235], v[104:107], v[0:15]
	s_waitcnt lgkmcnt(3)
	v_mfma_f32_32x32x16_bf16 v[48:63], v[216:219], v[108:111], v[48:63]
	s_waitcnt lgkmcnt(2)
	v_mfma_f32_32x32x16_bf16 v[32:47], v[220:223], v[108:111], v[32:47]
	s_waitcnt lgkmcnt(1)
	v_mfma_f32_32x32x16_bf16 v[64:79], v[224:227], v[108:111], v[64:79]
	s_waitcnt lgkmcnt(0)
	v_mfma_f32_32x32x16_bf16 v[80:95], v[228:231], v[108:111], v[80:95]
	v_mfma_f32_32x32x16_bf16 v[0:15], v[232:235], v[108:111], v[0:15]
	s_setprio 0
	s_andn2_b64 vcc, exec, s[8:9]
	s_cbranch_vccz .LBB0_386

; DI float xmax32(float x) { auto t = __builtin_amdgcn_permlane32_swap(__float_as_uint(x), __float_as_uint(x), false, false); return fmaxf(__uint_as_float(t[0]), __uint_as_float(t[1])); }
; template <int DK, int DV>
; DI void attn_map(f32x16 (&O)[DV / 32], float& lsum, const u16* qrow, const u16* K1, int ldk1, const u16* K2, int ldk2, const u16* Vt, int nkeys, char* smem) {
;     ...
;     float mx0 = fmaxf(fmaxf(s[0][0], s[0][1]), s[0][2]), mx1 = fmaxf(fmaxf(s[1][0], s[1][1]), s[1][2]);
; #pragma unroll
;     for (int i = 3; i < 15; i += 2) { mx0 = fmaxf(fmaxf(mx0, s[0][i]), s[0][i + 1]); mx1 = fmaxf(fmaxf(mx1, s[1][i]), s[1][i + 1]); }
;     float mx = fmaxf(fmaxf(mx0, mx1), fmaxf(s[0][15], s[1][15]));
;     mx = xmax32(mx);
;     const bool first = (k0 == 0);
;     if (first || __any(mx > 6.f)) {
;       float dl = first ? mx : fmaxf(mx, 0.f);
;       float alpha = __builtin_amdgcn_exp2f(-dl);
; #pragma unroll
;       for (int i = 0; i < 16; ++i) { negm[i] -= dl; lacc[i] *= alpha; }
; #pragma unroll
;       for (int dd = 0; dd < DV / 32; ++dd)
; #pragma unroll
;         for (int i = 0; i < 16; ++i) O[dd][i] *= alpha;
; #pragma unroll
;       for (int j = 0; j < 2; ++j)
; #pragma unroll
;         for (int i = 0; i < 16; ++i) s[j][i] -= dl;
;     }
.Lqk_join_A:
	s_nop 0
	v_max3_f32 v194, v96, v97, v98
	v_lshl_add_u64 v[176:177], v[176:177], 0, s[56:57]
	v_lshl_add_u64 v[178:179], v[178:179], 0, s[56:57]
	v_lshl_add_u64 v[180:181], v[180:181], 0, s[56:57]
	v_lshl_add_u64 v[182:183], v[182:183], 0, s[56:57]
	v_lshl_add_u64 v[184:185], v[184:185], 0, s[58:59]
	v_lshl_add_u64 v[186:187], v[186:187], 0, s[58:59]
	v_mov_b64_e32 v[232:233], s[48:49]
	v_mov_b64_e32 v[234:235], s[50:51]
	s_nop 0
	v_max3_f32 v195, v112, v113, v114
	v_max3_f32 v194, v194, v99, v100
	v_max3_f32 v195, v195, v115, v116
	v_max3_f32 v194, v194, v101, v102
	v_max3_f32 v195, v195, v117, v118
	v_max3_f32 v194, v194, v103, v104
	v_max3_f32 v195, v195, v119, v120
	v_max3_f32 v194, v194, v105, v106
	v_max3_f32 v195, v195, v121, v122
	v_max3_f32 v194, v194, v107, v108
	v_max3_f32 v195, v195, v123, v124
	v_max_f32_e32 v196, v127, v127
	v_max_f32_e32 v197, v111, v111
	v_max3_f32 v194, v194, v109, v110
	v_max3_f32 v195, v195, v125, v126
	v_max_f32_e32 v196, v197, v196
	v_max3_f32 v194, v194, v195, v196
	v_mov_b32_e32 v195, v194
	s_nop 1
	v_permlane32_swap_b32_e32 v194, v195
	v_max_f32_e32 v195, v195, v195
	v_max_f32_e32 v194, v194, v194
	v_max_f32_e32 v194, v194, v195
	v_cmp_lt_f32_e32 vcc, s45, v194
	s_cbranch_vccz .LBB0_381
	v_max_f32_e32 v194, v194, v194
	v_max_f32_e32 v195, 0, v194
	v_exp_f32_e64 v194, -v195
	v_sub_f32_e32 v31, v31, v195
	v_sub_f32_e32 v30, v30, v195
	v_sub_f32_e32 v29, v29, v195
	v_pk_mul_f32 v[62:63], v[62:63], v[194:195] op_sel_hi:[1,0]
	v_pk_mul_f32 v[60:61], v[60:61], v[194:195] op_sel_hi:[1,0]
	v_pk_mul_f32 v[58:59], v[58:59], v[194:195] op_sel_hi:[1,0]
	v_pk_mul_f32 v[56:57], v[56:57], v[194:195] op_sel_hi:[1,0]
	v_pk_mul_f32 v[54:55], v[54:55], v[194:195] op_sel_hi:[1,0]
	v_pk_mul_f32 v[52:53], v[52:53], v[194:195] op_sel_hi:[1,0]
	v_pk_mul_f32 v[50:51], v[50:51], v[194:195] op_sel_hi:[1,0]
	v_pk_mul_f32 v[48:49], v[48:49], v[194:195] op_sel_hi:[1,0]
	v_pk_mul_f32 v[46:47], v[46:47], v[194:195] op_sel_hi:[1,0]
	v_pk_mul_f32 v[44:45], v[44:45], v[194:195] op_sel_hi:[1,0]
	v_pk_mul_f32 v[42:43], v[42:43], v[194:195] op_sel_hi:[1,0]
	v_pk_mul_f32 v[40:41], v[40:41], v[194:195] op_sel_hi:[1,0]
	v_pk_mul_f32 v[38:39], v[38:39], v[194:195] op_sel_hi:[1,0]
	v_pk_mul_f32 v[36:37], v[36:37], v[194:195] op_sel_hi:[1,0]
	v_pk_mul_f32 v[34:35], v[34:35], v[194:195] op_sel_hi:[1,0]
	v_pk_mul_f32 v[32:33], v[32:33], v[194:195] op_sel_hi:[1,0]
	v_pk_mul_f32 v[78:79], v[78:79], v[194:195] op_sel_hi:[1,0]
	v_pk_mul_f32 v[76:77], v[76:77], v[194:195] op_sel_hi:[1,0]
	v_pk_mul_f32 v[74:75], v[74:75], v[194:195] op_sel_hi:[1,0]
	v_pk_mul_f32 v[72:73], v[72:73], v[194:195] op_sel_hi:[1,0]
	v_pk_mul_f32 v[70:71], v[70:71], v[194:195] op_sel_hi:[1,0]
	v_pk_mul_f32 v[68:69], v[68:69], v[194:195] op_sel_hi:[1,0]
	v_pk_mul_f32 v[66:67], v[66:67], v[194:195] op_sel_hi:[1,0]
	v_pk_mul_f32 v[64:65], v[64:65], v[194:195] op_sel_hi:[1,0]
	v_pk_mul_f32 v[94:95], v[94:95], v[194:195] op_sel_hi:[1,0]
	v_pk_mul_f32 v[92:93], v[92:93], v[194:195] op_sel_hi:[1,0]
	v_pk_mul_f32 v[90:91], v[90:91], v[194:195] op_sel_hi:[1,0]
	v_pk_mul_f32 v[88:89], v[88:89], v[194:195] op_sel_hi:[1,0]
	v_pk_mul_f32 v[86:87], v[86:87], v[194:195] op_sel_hi:[1,0]
	v_pk_mul_f32 v[84:85], v[84:85], v[194:195] op_sel_hi:[1,0]
	v_pk_mul_f32 v[82:83], v[82:83], v[194:195] op_sel_hi:[1,0]
	v_pk_mul_f32 v[80:81], v[80:81], v[194:195] op_sel_hi:[1,0]
	v_sub_f32_e32 v28, v28, v195
	v_sub_f32_e32 v27, v27, v195
	v_sub_f32_e32 v26, v26, v195
	v_sub_f32_e32 v25, v25, v195
	v_sub_f32_e32 v24, v24, v195
	v_sub_f32_e32 v23, v23, v195
	v_sub_f32_e32 v22, v22, v195
	v_sub_f32_e32 v21, v21, v195
	v_sub_f32_e32 v20, v20, v195
	v_sub_f32_e32 v19, v19, v195
	v_sub_f32_e32 v18, v18, v195
	v_sub_f32_e32 v17, v17, v195
	v_sub_f32_e32 v16, v16, v195
	v_sub_f32_e32 v96, v96, v195
	v_sub_f32_e32 v97, v97, v195
	v_sub_f32_e32 v98, v98, v195
	v_sub_f32_e32 v99, v99, v195
	v_sub_f32_e32 v100, v100, v195
	v_sub_f32_e32 v101, v101, v195
	v_sub_f32_e32 v102, v102, v195
	v_sub_f32_e32 v103, v103, v195
	v_sub_f32_e32 v104, v104, v195
	v_sub_f32_e32 v105, v105, v195
	v_sub_f32_e32 v106, v106, v195
	v_sub_f32_e32 v107, v107, v195
	v_sub_f32_e32 v108, v108, v195
	v_sub_f32_e32 v109, v109, v195
	v_sub_f32_e32 v110, v110, v195
	v_sub_f32_e32 v111, v111, v195
	v_sub_f32_e32 v112, v112, v195
	v_sub_f32_e32 v113, v113, v195
	v_sub_f32_e32 v114, v114, v195
	v_sub_f32_e32 v115, v115, v195
	v_sub_f32_e32 v116, v116, v195
	v_sub_f32_e32 v117, v117, v195
	v_sub_f32_e32 v118, v118, v195
	v_sub_f32_e32 v119, v119, v195
	v_sub_f32_e32 v120, v120, v195
	v_sub_f32_e32 v121, v121, v195
	v_sub_f32_e32 v122, v122, v195
	v_sub_f32_e32 v123, v123, v195
	v_sub_f32_e32 v124, v124, v195
	v_sub_f32_e32 v125, v125, v195
	v_sub_f32_e32 v126, v126, v195
	v_sub_f32_e32 v127, v127, v195
	v_pk_mul_f32 v[14:15], v[14:15], v[194:195] op_sel_hi:[1,0]
	v_pk_mul_f32 v[12:13], v[12:13], v[194:195] op_sel_hi:[1,0]
	v_pk_mul_f32 v[10:11], v[10:11], v[194:195] op_sel_hi:[1,0]
	v_pk_mul_f32 v[8:9], v[8:9], v[194:195] op_sel_hi:[1,0]
	v_pk_mul_f32 v[6:7], v[6:7], v[194:195] op_sel_hi:[1,0]
	v_pk_mul_f32 v[4:5], v[4:5], v[194:195] op_sel_hi:[1,0]
	v_pk_mul_f32 v[2:3], v[2:3], v[194:195] op_sel_hi:[1,0]
	v_pk_mul_f32 v[0:1], v[0:1], v[194:195] op_sel_hi:[1,0]
	s_branch .LBB0_381

; #define MFMA32(a, b, c) __builtin_amdgcn_mfma_f32_32x32x16_bf16((a), (b), (c), 0, 0, 0)
; DI unsigned pack2(float a, float b) { f32x2_t v = {a, b}; return __builtin_bit_cast(unsigned, __builtin_convertvector(v, bf16x2_t)); }
; template <int DK, int DV>
; DI void attn_map(f32x16 (&O)[DV / 32], float& lsum, const u16* qrow, const u16* K1, int ldk1, const u16* K2, int ldk2, const u16* Vt, int nkeys, char* smem) {
;     ...
;     bf16x8 pf[4];
; #pragma unroll
;     for (int j = 0; j < 2; ++j)
; #pragma unroll
;       for (int st = 0; st < 2; ++st) {
;         u32x4 pk;
;         pk.x = pack2(__builtin_amdgcn_exp2f(s[j][8 * st + 0]), __builtin_amdgcn_exp2f(s[j][8 * st + 1]));
;         pk.y = pack2(__builtin_amdgcn_exp2f(s[j][8 * st + 2]), __builtin_amdgcn_exp2f(s[j][8 * st + 3]));
;         pk.z = pack2(__builtin_amdgcn_exp2f(s[j][8 * st + 4]), __builtin_amdgcn_exp2f(s[j][8 * st + 5]));
;         pk.w = pack2(__builtin_amdgcn_exp2f(s[j][8 * st + 6]), __builtin_amdgcn_exp2f(s[j][8 * st + 7]));
;         pf[j * 2 + st] = __builtin_bit_cast(bf16x8, pk);
;       }
;     __builtin_amdgcn_s_setprio(1);
; #pragma unroll
;     for (int q = 0; q < 4; ++q) lacc = MFMA32(ones, pf[q], lacc);
; #pragma unroll
;     for (int dd = 0; dd < DV / 32; ++dd) {
; #pragma unroll
;       for (int q = 0; q < 4; ++q) {
;         bf16x8 vv = *(const bf16x8*)(Vs + (dd * 32 + r) * VST + q * 16 + 8 * h);
;         O[dd] = MFMA32(vv, pf[q], O[dd]);
;       }
;     }
;     {
;       constexpr int NPV = (DV / 32) * 4;
;       __builtin_amdgcn_sched_group_barrier(0x100, 2, 0);
; #pragma unroll
;       for (int q = 0; q < NPV - 2; ++q) { __builtin_amdgcn_sched_group_barrier(0x008, 1, 0); __builtin_amdgcn_sched_group_barrier(0x100, 1, 0); }
;       __builtin_amdgcn_sched_group_barrier(0x008, 6, 0);
;     }
;     __builtin_amdgcn_s_setprio(0);
.LBB0_403:
	s_add_i32 s10, s10, 64
	v_exp_f32_e32 v96, v96
	v_exp_f32_e32 v97, v97
	v_exp_f32_e32 v98, v98
	v_exp_f32_e32 v99, v99
	v_exp_f32_e32 v100, v100
	v_exp_f32_e32 v101, v101
	v_exp_f32_e32 v102, v102
	v_exp_f32_e32 v103, v103
	v_cvt_pk_bf16_f32 v96, v96, v97
	v_cvt_pk_bf16_f32 v97, v98, v99
	v_cvt_pk_bf16_f32 v98, v100, v101
	v_cvt_pk_bf16_f32 v99, v102, v103
	s_setprio 1
	s_waitcnt lgkmcnt(0)
	v_mfma_f32_32x32x16_bf16 v[48:63], v[200:203], v[96:99], v[48:63]
	ds_read_b128 v[200:203], v195 offset:9280
	v_exp_f32_e32 v100, v104
	v_exp_f32_e32 v101, v105
	v_mfma_f32_32x32x16_bf16 v[32:47], v[204:207], v[96:99], v[32:47]
	ds_read_b128 v[204:207], v195 offset:13888
	v_cvt_pk_bf16_f32 v100, v100, v101
	v_exp_f32_e32 v102, v106
	v_exp_f32_e32 v103, v107
	v_mfma_f32_32x32x16_bf16 v[16:31], v[208:211], v[96:99], v[16:31]
	ds_read_b128 v[208:211], v195 offset:18496
	v_cvt_pk_bf16_f32 v101, v102, v103
	v_exp_f32_e32 v104, v108
	v_exp_f32_e32 v105, v109
	v_exp_f32_e32 v106, v110
	v_mfma_f32_32x32x16_bf16 v[0:15], v[212:215], v[96:99], v[0:15]
	v_exp_f32_e32 v107, v111
	v_cvt_pk_bf16_f32 v102, v104, v105
	v_cvt_pk_bf16_f32 v103, v106, v107
	ds_read_b128 v[212:215], v195 offset:23104
	v_mfma_f32_32x32x16_bf16 v[64:79], v[232:235], v[96:99], v[64:79]
	v_mfma_f32_32x32x16_bf16 v[48:63], v[216:219], v[100:103], v[48:63]
	ds_read_b128 v[216:219], v195 offset:9312
	v_exp_f32_e32 v104, v112
	v_exp_f32_e32 v105, v113
	v_mfma_f32_32x32x16_bf16 v[32:47], v[220:223], v[100:103], v[32:47]
	ds_read_b128 v[220:223], v195 offset:13920
	v_cvt_pk_bf16_f32 v104, v104, v105
	v_exp_f32_e32 v106, v114
	v_exp_f32_e32 v107, v115
	v_mfma_f32_32x32x16_bf16 v[16:31], v[224:227], v[100:103], v[16:31]
	ds_read_b128 v[224:227], v195 offset:18528
	v_cvt_pk_bf16_f32 v105, v106, v107
	v_exp_f32_e32 v108, v116
	v_exp_f32_e32 v109, v117
	v_exp_f32_e32 v110, v118
	v_mfma_f32_32x32x16_bf16 v[0:15], v[228:231], v[100:103], v[0:15]
	v_exp_f32_e32 v111, v119
	v_cvt_pk_bf16_f32 v106, v108, v109
	v_cvt_pk_bf16_f32 v107, v110, v111
	ds_read_b128 v[228:231], v195 offset:23136
	v_mfma_f32_32x32x16_bf16 v[64:79], v[232:235], v[100:103], v[64:79]
	s_waitcnt lgkmcnt(7)
	v_mfma_f32_32x32x16_bf16 v[48:63], v[200:203], v[104:107], v[48:63]
	v_exp_f32_e32 v108, v120
	v_exp_f32_e32 v109, v121
	s_waitcnt lgkmcnt(6)
	v_mfma_f32_32x32x16_bf16 v[32:47], v[204:207], v[104:107], v[32:47]
	v_cvt_pk_bf16_f32 v108, v108, v109
	v_exp_f32_e32 v110, v122
	v_exp_f32_e32 v111, v123
	s_waitcnt lgkmcnt(5)
	v_mfma_f32_32x32x16_bf16 v[16:31], v[208:211], v[104:107], v[16:31]
	v_cvt_pk_bf16_f32 v109, v110, v111
	v_exp_f32_e32 v112, v124
	v_exp_f32_e32 v113, v125
	v_exp_f32_e32 v114, v126
	s_waitcnt lgkmcnt(4)
	v_mfma_f32_32x32x16_bf16 v[0:15], v[212:215], v[104:107], v[0:15]
	v_exp_f32_e32 v115, v127
	v_cvt_pk_bf16_f32 v110, v112, v113
	v_cvt_pk_bf16_f32 v111, v114, v115
	s_nop 0
	v_mfma_f32_32x32x16_bf16 v[64:79], v[232:235], v[104:107], v[64:79]
	s_waitcnt lgkmcnt(3)
	v_mfma_f32_32x32x16_bf16 v[48:63], v[216:219], v[108:111], v[48:63]
	s_waitcnt lgkmcnt(2)
	v_mfma_f32_32x32x16_bf16 v[32:47], v[220:223], v[108:111], v[32:47]
	s_waitcnt lgkmcnt(1)
	v_mfma_f32_32x32x16_bf16 v[16:31], v[224:227], v[108:111], v[16:31]
	s_waitcnt lgkmcnt(0)
	v_mfma_f32_32x32x16_bf16 v[0:15], v[228:231], v[108:111], v[0:15]
	v_mfma_f32_32x32x16_bf16 v[64:79], v[232:235], v[108:111], v[64:79]
	s_setprio 0
	s_andn2_b64 vcc, exec, s[6:7]
	s_cbranch_vccz .LBB0_408

; DI float xmax32(float x) { auto t = __builtin_amdgcn_permlane32_swap(__float_as_uint(x), __float_as_uint(x), false, false); return fmaxf(__uint_as_float(t[0]), __uint_as_float(t[1])); }
; template <int DK, int DV>
; DI void attn_map(f32x16 (&O)[DV / 32], float& lsum, const u16* qrow, const u16* K1, int ldk1, const u16* K2, int ldk2, const u16* Vt, int nkeys, char* smem) {
;     ...
;     float mx0 = fmaxf(fmaxf(s[0][0], s[0][1]), s[0][2]), mx1 = fmaxf(fmaxf(s[1][0], s[1][1]), s[1][2]);
; #pragma unroll
;     for (int i = 3; i < 15; i += 2) { mx0 = fmaxf(fmaxf(mx0, s[0][i]), s[0][i + 1]); mx1 = fmaxf(fmaxf(mx1, s[1][i]), s[1][i + 1]); }
;     float mx = fmaxf(fmaxf(mx0, mx1), fmaxf(s[0][15], s[1][15]));
;     mx = xmax32(mx);
;     const bool first = (k0 == 0);
;     if (first || __any(mx > 6.f)) {
;       float dl = first ? mx : fmaxf(mx, 0.f);
;       float alpha = __builtin_amdgcn_exp2f(-dl);
; #pragma unroll
;       for (int i = 0; i < 16; ++i) { negm[i] -= dl; lacc[i] *= alpha; }
; #pragma unroll
;       for (int dd = 0; dd < DV / 32; ++dd)
; #pragma unroll
;         for (int i = 0; i < 16; ++i) O[dd][i] *= alpha;
; #pragma unroll
;       for (int j = 0; j < 2; ++j)
; #pragma unroll
;         for (int i = 0; i < 16; ++i) s[j][i] -= dl;
;     }
.Lqk_join_B:
	s_nop 0
	v_max3_f32 v196, v96, v97, v98
	v_lshl_add_u64 v[176:177], v[176:177], 0, s[56:57]
	v_lshl_add_u64 v[178:179], v[178:179], 0, s[56:57]
	v_lshl_add_u64 v[180:181], v[180:181], 0, s[56:57]
	v_lshl_add_u64 v[182:183], v[182:183], 0, s[56:57]
	v_lshl_add_u64 v[184:185], v[184:185], 0, s[58:59]
	v_lshl_add_u64 v[186:187], v[186:187], 0, s[58:59]
	v_mov_b64_e32 v[232:233], s[48:49]
	v_mov_b64_e32 v[234:235], s[50:51]
	s_nop 0
	v_max3_f32 v197, v112, v113, v114
	v_max3_f32 v196, v196, v99, v100
	v_max3_f32 v197, v197, v115, v116
	v_max3_f32 v196, v196, v101, v102
	v_max3_f32 v197, v197, v117, v118
	v_max3_f32 v196, v196, v103, v104
	v_max3_f32 v197, v197, v119, v120
	v_max3_f32 v196, v196, v105, v106
	v_max3_f32 v197, v197, v121, v122
	v_max3_f32 v196, v196, v107, v108
	v_max3_f32 v197, v197, v123, v124
	v_max_f32_e32 v198, v127, v127
	v_max_f32_e32 v199, v111, v111
	v_max3_f32 v196, v196, v109, v110
	v_max3_f32 v197, v197, v125, v126
	v_max_f32_e32 v198, v199, v198
	v_max3_f32 v196, v196, v197, v198
	v_mov_b32_e32 v197, v196
	s_nop 1
	v_permlane32_swap_b32_e32 v196, v197
	v_max_f32_e32 v197, v197, v197
	v_max_f32_e32 v196, v196, v196
	v_max_f32_e32 v196, v196, v197
	v_cmp_lt_f32_e32 vcc, s45, v196
	s_cbranch_vccz .LBB0_403
	v_max_f32_e32 v196, v196, v196
	v_max_f32_e32 v197, 0, v196
	v_exp_f32_e64 v196, -v197
	v_sub_f32_e32 v95, v95, v197
	v_sub_f32_e32 v94, v94, v197
	v_sub_f32_e32 v93, v93, v197
	v_pk_mul_f32 v[62:63], v[62:63], v[196:197] op_sel_hi:[1,0]
	v_pk_mul_f32 v[60:61], v[60:61], v[196:197] op_sel_hi:[1,0]
	v_pk_mul_f32 v[58:59], v[58:59], v[196:197] op_sel_hi:[1,0]
	v_pk_mul_f32 v[56:57], v[56:57], v[196:197] op_sel_hi:[1,0]
	v_pk_mul_f32 v[54:55], v[54:55], v[196:197] op_sel_hi:[1,0]
	v_pk_mul_f32 v[52:53], v[52:53], v[196:197] op_sel_hi:[1,0]
	v_pk_mul_f32 v[50:51], v[50:51], v[196:197] op_sel_hi:[1,0]
	v_pk_mul_f32 v[48:49], v[48:49], v[196:197] op_sel_hi:[1,0]
	v_pk_mul_f32 v[46:47], v[46:47], v[196:197] op_sel_hi:[1,0]
	v_pk_mul_f32 v[44:45], v[44:45], v[196:197] op_sel_hi:[1,0]
	v_pk_mul_f32 v[42:43], v[42:43], v[196:197] op_sel_hi:[1,0]
	v_pk_mul_f32 v[40:41], v[40:41], v[196:197] op_sel_hi:[1,0]
	v_pk_mul_f32 v[38:39], v[38:39], v[196:197] op_sel_hi:[1,0]
	v_pk_mul_f32 v[36:37], v[36:37], v[196:197] op_sel_hi:[1,0]
	v_pk_mul_f32 v[34:35], v[34:35], v[196:197] op_sel_hi:[1,0]
	v_pk_mul_f32 v[32:33], v[32:33], v[196:197] op_sel_hi:[1,0]
	v_pk_mul_f32 v[30:31], v[30:31], v[196:197] op_sel_hi:[1,0]
	v_pk_mul_f32 v[28:29], v[28:29], v[196:197] op_sel_hi:[1,0]
	v_pk_mul_f32 v[26:27], v[26:27], v[196:197] op_sel_hi:[1,0]
	v_pk_mul_f32 v[24:25], v[24:25], v[196:197] op_sel_hi:[1,0]
	v_pk_mul_f32 v[22:23], v[22:23], v[196:197] op_sel_hi:[1,0]
	v_pk_mul_f32 v[20:21], v[20:21], v[196:197] op_sel_hi:[1,0]
	v_pk_mul_f32 v[18:19], v[18:19], v[196:197] op_sel_hi:[1,0]
	v_pk_mul_f32 v[16:17], v[16:17], v[196:197] op_sel_hi:[1,0]
	v_pk_mul_f32 v[14:15], v[14:15], v[196:197] op_sel_hi:[1,0]
	v_pk_mul_f32 v[12:13], v[12:13], v[196:197] op_sel_hi:[1,0]
	v_pk_mul_f32 v[10:11], v[10:11], v[196:197] op_sel_hi:[1,0]
	v_pk_mul_f32 v[8:9], v[8:9], v[196:197] op_sel_hi:[1,0]
	v_pk_mul_f32 v[6:7], v[6:7], v[196:197] op_sel_hi:[1,0]
	v_pk_mul_f32 v[4:5], v[4:5], v[196:197] op_sel_hi:[1,0]
	v_pk_mul_f32 v[2:3], v[2:3], v[196:197] op_sel_hi:[1,0]
	v_pk_mul_f32 v[0:1], v[0:1], v[196:197] op_sel_hi:[1,0]
	v_sub_f32_e32 v92, v92, v197
	v_sub_f32_e32 v91, v91, v197
	v_sub_f32_e32 v90, v90, v197
	v_sub_f32_e32 v89, v89, v197
	v_sub_f32_e32 v88, v88, v197
	v_sub_f32_e32 v87, v87, v197
	v_sub_f32_e32 v86, v86, v197
	v_sub_f32_e32 v85, v85, v197
	v_sub_f32_e32 v84, v84, v197
	v_sub_f32_e32 v83, v83, v197
	v_sub_f32_e32 v82, v82, v197
	v_sub_f32_e32 v81, v81, v197
	v_sub_f32_e32 v80, v80, v197
	v_sub_f32_e32 v96, v96, v197
	v_sub_f32_e32 v97, v97, v197
	v_sub_f32_e32 v98, v98, v197
	v_sub_f32_e32 v99, v99, v197
	v_sub_f32_e32 v100, v100, v197
	v_sub_f32_e32 v101, v101, v197
	v_sub_f32_e32 v102, v102, v197
	v_sub_f32_e32 v103, v103, v197
	v_sub_f32_e32 v104, v104, v197
	v_sub_f32_e32 v105, v105, v197
	v_sub_f32_e32 v106, v106, v197
	v_sub_f32_e32 v107, v107, v197
	v_sub_f32_e32 v108, v108, v197
	v_sub_f32_e32 v109, v109, v197
	v_sub_f32_e32 v110, v110, v197
	v_sub_f32_e32 v111, v111, v197
	v_sub_f32_e32 v112, v112, v197
	v_sub_f32_e32 v113, v113, v197
	v_sub_f32_e32 v114, v114, v197
	v_sub_f32_e32 v115, v115, v197
	v_sub_f32_e32 v116, v116, v197
	v_sub_f32_e32 v117, v117, v197
	v_sub_f32_e32 v118, v118, v197
	v_sub_f32_e32 v119, v119, v197
	v_sub_f32_e32 v120, v120, v197
	v_sub_f32_e32 v121, v121, v197
	v_sub_f32_e32 v122, v122, v197
	v_sub_f32_e32 v123, v123, v197
	v_sub_f32_e32 v124, v124, v197
	v_sub_f32_e32 v125, v125, v197
	v_sub_f32_e32 v126, v126, v197
	v_sub_f32_e32 v127, v127, v197
	v_pk_mul_f32 v[78:79], v[78:79], v[196:197] op_sel_hi:[1,0]
	v_pk_mul_f32 v[76:77], v[76:77], v[196:197] op_sel_hi:[1,0]
	v_pk_mul_f32 v[74:75], v[74:75], v[196:197] op_sel_hi:[1,0]
	v_pk_mul_f32 v[72:73], v[72:73], v[196:197] op_sel_hi:[1,0]
	v_pk_mul_f32 v[70:71], v[70:71], v[196:197] op_sel_hi:[1,0]
	v_pk_mul_f32 v[68:69], v[68:69], v[196:197] op_sel_hi:[1,0]
	v_pk_mul_f32 v[66:67], v[66:67], v[196:197] op_sel_hi:[1,0]
	v_pk_mul_f32 v[64:65], v[64:65], v[196:197] op_sel_hi:[1,0]
	s_branch .LBB0_403

; template <int DK, int DV>
; DI void attn_map(f32x16 (&O)[DV / 32], float& lsum, const u16* qrow, const u16* K1, int ldk1, const u16* K2, int ldk2, const u16* Vt, int nkeys, char* smem) {
;     ...
;     float mx0 = fmaxf(fmaxf(s[0][0], s[0][1]), s[0][2]), mx1 = fmaxf(fmaxf(s[1][0], s[1][1]), s[1][2]);
; #pragma unroll
;     for (int i = 3; i < 15; i += 2) { mx0 = fmaxf(fmaxf(mx0, s[0][i]), s[0][i + 1]); mx1 = fmaxf(fmaxf(mx1, s[1][i]), s[1][i + 1]); }
;     float mx = fmaxf(fmaxf(mx0, mx1), fmaxf(s[0][15], s[1][15]));
;     mx = xmax32(mx);
;     const bool first = (k0 == 0);
;     if (first || __any(mx > 6.f)) {
;       float dl = first ? mx : fmaxf(mx, 0.f);
;       float alpha = __builtin_amdgcn_exp2f(-dl);
; #pragma unroll
;       for (int i = 0; i < 16; ++i) { negm[i] -= dl; lacc[i] *= alpha; }
; #pragma unroll
;       for (int dd = 0; dd < DV / 32; ++dd)
; #pragma unroll
;         for (int i = 0; i < 16; ++i) O[dd][i] *= alpha;
; #pragma unroll
;       for (int j = 0; j < 2; ++j)
; #pragma unroll
;         for (int i = 0; i < 16; ++i) s[j][i] -= dl;
;     }
;     bf16x8 pf[4];
; #pragma unroll
;     for (int j = 0; j < 2; ++j)
; #pragma unroll
;       for (int st = 0; st < 2; ++st) {
;         u32x4 pk;
;         pk.x = pack2(__builtin_amdgcn_exp2f(s[j][8 * st + 0]), __builtin_amdgcn_exp2f(s[j][8 * st + 1]));
;         pk.y = pack2(__builtin_amdgcn_exp2f(s[j][8 * st + 2]), __builtin_amdgcn_exp2f(s[j][8 * st + 3]));
;         pk.z = pack2(__builtin_amdgcn_exp2f(s[j][8 * st + 4]), __builtin_amdgcn_exp2f(s[j][8 * st + 5]));
;         pk.w = pack2(__builtin_amdgcn_exp2f(s[j][8 * st + 6]), __builtin_amdgcn_exp2f(s[j][8 * st + 7]));
;         pf[j * 2 + st] = __builtin_bit_cast(bf16x8, pk);
;       }
;     __builtin_amdgcn_s_setprio(1);
; #pragma unroll
;     for (int q = 0; q < 4; ++q) lacc = MFMA32(ones, pf[q], lacc);
; #pragma unroll
;     for (int dd = 0; dd < DV / 32; ++dd) {
; #pragma unroll
;       for (int q = 0; q < 4; ++q) {
;         bf16x8 vv = *(const bf16x8*)(Vs + (dd * 32 + r) * VST + q * 16 + 8 * h);
;         O[dd] = MFMA32(vv, pf[q], O[dd]);
;       }
;     }
;     {
;       constexpr int NPV = (DV / 32) * 4;
;       __builtin_amdgcn_sched_group_barrier(0x100, 2, 0);
; #pragma unroll
;       for (int q = 0; q < NPV - 2; ++q) { __builtin_amdgcn_sched_group_barrier(0x008, 1, 0); __builtin_amdgcn_sched_group_barrier(0x100, 1, 0); }
.Lqk_join_C:
	v_max3_f32 v173, v64, v65, v66
	v_lshl_add_u64 v[154:155], v[154:155], 0, s[56:57]
	v_lshl_add_u64 v[156:157], v[156:157], 0, s[56:57]
	v_mov_b64_e32 v[184:185], s[48:49]
	v_mov_b64_e32 v[186:187], s[50:51]
	s_nop 5
	v_max3_f32 v174, v80, v81, v82
	v_max3_f32 v173, v173, v67, v68
	v_max3_f32 v174, v174, v83, v84
	v_max3_f32 v173, v173, v69, v70
	v_max3_f32 v174, v174, v85, v86
	v_max3_f32 v173, v173, v71, v72
	v_max3_f32 v174, v174, v87, v88
	v_max3_f32 v173, v173, v73, v74
	v_max3_f32 v174, v174, v89, v90
	v_max3_f32 v173, v173, v75, v76
	v_max3_f32 v174, v174, v91, v92
	v_max_f32_e32 v175, v95, v95
	v_max_f32_e32 v176, v79, v79
	v_max3_f32 v173, v173, v77, v78
	v_max3_f32 v174, v174, v93, v94
	v_max_f32_e32 v175, v176, v175
	v_max3_f32 v173, v173, v174, v175
	v_mov_b32_e32 v174, v173
	s_nop 1
	v_permlane32_swap_b32_e32 v173, v174
	v_max_f32_e32 v174, v174, v174
	v_max_f32_e32 v173, v173, v173
	v_max_f32_e32 v173, v173, v174
	v_cmp_lt_f32_e32 vcc, s45, v173
	s_cbranch_vccz .LBB0_440
	v_max_f32_e32 v173, v173, v173
	v_max_f32_e32 v173, 0, v173
	v_exp_f32_e64 v174, -v173
	v_sub_f32_e32 v31, v31, v173
	v_sub_f32_e32 v30, v30, v173
	v_sub_f32_e32 v29, v29, v173
	v_pk_mul_f32 v[62:63], v[62:63], v[174:175] op_sel_hi:[1,0]
	v_pk_mul_f32 v[60:61], v[60:61], v[174:175] op_sel_hi:[1,0]
	v_pk_mul_f32 v[58:59], v[58:59], v[174:175] op_sel_hi:[1,0]
	v_pk_mul_f32 v[56:57], v[56:57], v[174:175] op_sel_hi:[1,0]
	v_pk_mul_f32 v[54:55], v[54:55], v[174:175] op_sel_hi:[1,0]
	v_pk_mul_f32 v[52:53], v[52:53], v[174:175] op_sel_hi:[1,0]
	v_pk_mul_f32 v[50:51], v[50:51], v[174:175] op_sel_hi:[1,0]
	v_pk_mul_f32 v[48:49], v[48:49], v[174:175] op_sel_hi:[1,0]
	v_pk_mul_f32 v[46:47], v[46:47], v[174:175] op_sel_hi:[1,0]
	v_pk_mul_f32 v[44:45], v[44:45], v[174:175] op_sel_hi:[1,0]
	v_pk_mul_f32 v[42:43], v[42:43], v[174:175] op_sel_hi:[1,0]
	v_pk_mul_f32 v[40:41], v[40:41], v[174:175] op_sel_hi:[1,0]
	v_pk_mul_f32 v[38:39], v[38:39], v[174:175] op_sel_hi:[1,0]
	v_pk_mul_f32 v[36:37], v[36:37], v[174:175] op_sel_hi:[1,0]
	v_pk_mul_f32 v[34:35], v[34:35], v[174:175] op_sel_hi:[1,0]
	v_pk_mul_f32 v[32:33], v[32:33], v[174:175] op_sel_hi:[1,0]
	v_sub_f32_e32 v28, v28, v173
	v_sub_f32_e32 v27, v27, v173
	v_sub_f32_e32 v26, v26, v173
	v_sub_f32_e32 v25, v25, v173
	v_sub_f32_e32 v24, v24, v173
	v_sub_f32_e32 v23, v23, v173
	v_sub_f32_e32 v22, v22, v173
	v_sub_f32_e32 v21, v21, v173
	v_sub_f32_e32 v20, v20, v173
	v_sub_f32_e32 v19, v19, v173
	v_sub_f32_e32 v18, v18, v173
	v_sub_f32_e32 v17, v17, v173
	v_sub_f32_e32 v16, v16, v173
	v_sub_f32_e32 v64, v64, v173
	v_sub_f32_e32 v65, v65, v173
	v_sub_f32_e32 v66, v66, v173
	v_sub_f32_e32 v67, v67, v173
	v_sub_f32_e32 v68, v68, v173
	v_sub_f32_e32 v69, v69, v173
	v_sub_f32_e32 v70, v70, v173
	v_sub_f32_e32 v71, v71, v173
	v_sub_f32_e32 v72, v72, v173
	v_sub_f32_e32 v73, v73, v173
	v_sub_f32_e32 v74, v74, v173
	v_sub_f32_e32 v75, v75, v173
	v_sub_f32_e32 v76, v76, v173
	v_sub_f32_e32 v77, v77, v173
	v_sub_f32_e32 v78, v78, v173
	v_sub_f32_e32 v79, v79, v173
	v_sub_f32_e32 v80, v80, v173
	v_sub_f32_e32 v81, v81, v173
	v_sub_f32_e32 v82, v82, v173
	v_sub_f32_e32 v83, v83, v173
	v_sub_f32_e32 v84, v84, v173
	v_sub_f32_e32 v85, v85, v173
	v_sub_f32_e32 v86, v86, v173
	v_sub_f32_e32 v87, v87, v173
	v_sub_f32_e32 v88, v88, v173
	v_sub_f32_e32 v89, v89, v173
	v_sub_f32_e32 v90, v90, v173
	v_sub_f32_e32 v91, v91, v173
	v_sub_f32_e32 v92, v92, v173
	v_sub_f32_e32 v93, v93, v173
	v_sub_f32_e32 v94, v94, v173
	v_sub_f32_e32 v95, v95, v173
	v_pk_mul_f32 v[14:15], v[14:15], v[174:175] op_sel_hi:[1,0]
	v_pk_mul_f32 v[12:13], v[12:13], v[174:175] op_sel_hi:[1,0]
	v_pk_mul_f32 v[10:11], v[10:11], v[174:175] op_sel_hi:[1,0]
	v_pk_mul_f32 v[8:9], v[8:9], v[174:175] op_sel_hi:[1,0]
	v_pk_mul_f32 v[6:7], v[6:7], v[174:175] op_sel_hi:[1,0]
	v_pk_mul_f32 v[4:5], v[4:5], v[174:175] op_sel_hi:[1,0]
	v_pk_mul_f32 v[2:3], v[2:3], v[174:175] op_sel_hi:[1,0]
	v_pk_mul_f32 v[0:1], v[0:1], v[174:175] op_sel_hi:[1,0]
.LBB0_440:
	v_exp_f32_e32 v64, v64
	v_exp_f32_e32 v65, v65
	v_exp_f32_e32 v66, v66
	v_exp_f32_e32 v67, v67
	v_exp_f32_e32 v68, v68
	v_exp_f32_e32 v69, v69
	v_exp_f32_e32 v70, v70
	v_exp_f32_e32 v71, v71
	v_cvt_pk_bf16_f32 v64, v64, v65
	v_cvt_pk_bf16_f32 v65, v66, v67
	v_cvt_pk_bf16_f32 v66, v68, v69
	v_cvt_pk_bf16_f32 v67, v70, v71
	s_setprio 1
	s_waitcnt lgkmcnt(0)
	v_mfma_f32_32x32x16_bf16 v[48:63], v[190:193], v[64:67], v[48:63]
	v_exp_f32_e32 v68, v72
	v_exp_f32_e32 v69, v73
	v_exp_f32_e32 v70, v74
	v_exp_f32_e32 v71, v75
	v_mfma_f32_32x32x16_bf16 v[32:47], v[194:197], v[64:67], v[32:47]
	v_cvt_pk_bf16_f32 v68, v68, v69
	v_cvt_pk_bf16_f32 v69, v70, v71
	v_exp_f32_e32 v72, v76
	v_exp_f32_e32 v73, v77
	v_exp_f32_e32 v74, v78
	v_mfma_f32_32x32x16_bf16 v[0:15], v[184:187], v[64:67], v[0:15]
	v_exp_f32_e32 v75, v79
	v_cvt_pk_bf16_f32 v70, v72, v73
	v_cvt_pk_bf16_f32 v71, v74, v75
	s_nop 0
	s_nop 0
	v_mfma_f32_32x32x16_bf16 v[48:63], v[198:201], v[68:71], v[48:63]
	v_exp_f32_e32 v72, v80
	v_exp_f32_e32 v73, v81
	v_exp_f32_e32 v74, v82
	v_exp_f32_e32 v75, v83
	v_mfma_f32_32x32x16_bf16 v[32:47], v[202:205], v[68:71], v[32:47]
	v_cvt_pk_bf16_f32 v72, v72, v73
	v_cvt_pk_bf16_f32 v73, v74, v75
	v_exp_f32_e32 v76, v84
	v_exp_f32_e32 v77, v85
	v_exp_f32_e32 v78, v86
	v_mfma_f32_32x32x16_bf16 v[0:15], v[184:187], v[68:71], v[0:15]
	v_exp_f32_e32 v79, v87
	v_cvt_pk_bf16_f32 v74, v76, v77
	v_cvt_pk_bf16_f32 v75, v78, v79
	s_nop 0
	s_nop 0
	v_mfma_f32_32x32x16_bf16 v[48:63], v[206:209], v[72:75], v[48:63]
	v_exp_f32_e32 v76, v88
	v_exp_f32_e32 v77, v89
	v_exp_f32_e32 v78, v90
	v_exp_f32_e32 v79, v91
	v_mfma_f32_32x32x16_bf16 v[32:47], v[210:213], v[72:75], v[32:47]
	v_cvt_pk_bf16_f32 v76, v76, v77
	v_cvt_pk_bf16_f32 v77, v78, v79
	v_exp_f32_e32 v80, v92
	v_exp_f32_e32 v81, v93
	v_exp_f32_e32 v82, v94
	v_mfma_f32_32x32x16_bf16 v[0:15], v[184:187], v[72:75], v[0:15]
	v_exp_f32_e32 v83, v95
	v_cvt_pk_bf16_f32 v78, v80, v81
	v_cvt_pk_bf16_f32 v79, v82, v83
	s_nop 0
	s_nop 0
	v_mfma_f32_32x32x16_bf16 v[48:63], v[214:217], v[76:79], v[48:63]
	v_mfma_f32_32x32x16_bf16 v[32:47], v[218:221], v[76:79], v[32:47]
	v_mfma_f32_32x32x16_bf16 v[0:15], v[184:187], v[76:79], v[0:15]
	s_setprio 0
	s_andn2_b64 vcc, exec, s[8:9]
	s_cbranch_vccz .LBB0_442
	s_mov_b64 s[10:11], s[6:7]
	s_branch .LBB0_436

; #define MFMA32(a, b, c) __builtin_amdgcn_mfma_f32_32x32x16_bf16((a), (b), (c), 0, 0, 0)
; DI unsigned pack2(float a, float b) { f32x2_t v = {a, b}; return __builtin_bit_cast(unsigned, __builtin_convertvector(v, bf16x2_t)); }
; template <int DK, int DV>
; DI void attn_map(f32x16 (&O)[DV / 32], float& lsum, const u16* qrow, const u16* K1, int ldk1, const u16* K2, int ldk2, const u16* Vt, int nkeys, char* smem) {
;     ...
;     bf16x8 pf[4];
; #pragma unroll
;     for (int j = 0; j < 2; ++j)
; #pragma unroll
;       for (int st = 0; st < 2; ++st) {
;         u32x4 pk;
;         pk.x = pack2(__builtin_amdgcn_exp2f(s[j][8 * st + 0]), __builtin_amdgcn_exp2f(s[j][8 * st + 1]));
;         pk.y = pack2(__builtin_amdgcn_exp2f(s[j][8 * st + 2]), __builtin_amdgcn_exp2f(s[j][8 * st + 3]));
;         pk.z = pack2(__builtin_amdgcn_exp2f(s[j][8 * st + 4]), __builtin_amdgcn_exp2f(s[j][8 * st + 5]));
;         pk.w = pack2(__builtin_amdgcn_exp2f(s[j][8 * st + 6]), __builtin_amdgcn_exp2f(s[j][8 * st + 7]));
;         pf[j * 2 + st] = __builtin_bit_cast(bf16x8, pk);
;       }
;     __builtin_amdgcn_s_setprio(1);
; #pragma unroll
;     for (int q = 0; q < 4; ++q) lacc = MFMA32(ones, pf[q], lacc);
; #pragma unroll
;     for (int dd = 0; dd < DV / 32; ++dd) {
; #pragma unroll
;       for (int q = 0; q < 4; ++q) {
;         bf16x8 vv = *(const bf16x8*)(Vs + (dd * 32 + r) * VST + q * 16 + 8 * h);
;         O[dd] = MFMA32(vv, pf[q], O[dd]);
;       }
;     }
;     {
;       constexpr int NPV = (DV / 32) * 4;
;       __builtin_amdgcn_sched_group_barrier(0x100, 2, 0);
; #pragma unroll
;       for (int q = 0; q < NPV - 2; ++q) { __builtin_amdgcn_sched_group_barrier(0x008, 1, 0); __builtin_amdgcn_sched_group_barrier(0x100, 1, 0); }
;       __builtin_amdgcn_sched_group_barrier(0x008, 6, 0);
;     }
;     __builtin_amdgcn_s_setprio(0);
.LBB0_446:
	s_add_i32 s12, s12, 64
	v_exp_f32_e32 v64, v64
	v_exp_f32_e32 v65, v65
	v_exp_f32_e32 v66, v66
	v_exp_f32_e32 v67, v67
	v_exp_f32_e32 v68, v68
	v_exp_f32_e32 v69, v69
	v_exp_f32_e32 v70, v70
	v_exp_f32_e32 v71, v71
	v_cvt_pk_bf16_f32 v64, v64, v65
	v_cvt_pk_bf16_f32 v65, v66, v67
	v_cvt_pk_bf16_f32 v66, v68, v69
	v_cvt_pk_bf16_f32 v67, v70, v71
	s_setprio 1
	s_waitcnt lgkmcnt(0)
	v_mfma_f32_32x32x16_bf16 v[48:63], v[200:203], v[64:67], v[48:63]
	v_exp_f32_e32 v68, v72
	v_exp_f32_e32 v69, v73
	v_exp_f32_e32 v70, v74
	v_exp_f32_e32 v71, v75
	v_mfma_f32_32x32x16_bf16 v[32:47], v[204:207], v[64:67], v[32:47]
	v_cvt_pk_bf16_f32 v68, v68, v69
	v_cvt_pk_bf16_f32 v69, v70, v71
	v_exp_f32_e32 v72, v76
	v_exp_f32_e32 v73, v77
	v_exp_f32_e32 v74, v78
	v_mfma_f32_32x32x16_bf16 v[0:15], v[232:235], v[64:67], v[0:15]
	v_exp_f32_e32 v75, v79
	v_cvt_pk_bf16_f32 v70, v72, v73
	v_cvt_pk_bf16_f32 v71, v74, v75
	s_nop 0
	s_nop 0
	v_mfma_f32_32x32x16_bf16 v[48:63], v[208:211], v[68:71], v[48:63]
	v_exp_f32_e32 v72, v80
	v_exp_f32_e32 v73, v81
	v_exp_f32_e32 v74, v82
	v_exp_f32_e32 v75, v83
	v_mfma_f32_32x32x16_bf16 v[32:47], v[212:215], v[68:71], v[32:47]
	v_cvt_pk_bf16_f32 v72, v72, v73
	v_cvt_pk_bf16_f32 v73, v74, v75
	v_exp_f32_e32 v76, v84
	v_exp_f32_e32 v77, v85
	v_exp_f32_e32 v78, v86
	v_mfma_f32_32x32x16_bf16 v[0:15], v[232:235], v[68:71], v[0:15]
	v_exp_f32_e32 v79, v87
	v_cvt_pk_bf16_f32 v74, v76, v77
	v_cvt_pk_bf16_f32 v75, v78, v79
	s_nop 0
	s_nop 0
	v_mfma_f32_32x32x16_bf16 v[48:63], v[216:219], v[72:75], v[48:63]
	v_exp_f32_e32 v76, v88
	v_exp_f32_e32 v77, v89
	v_exp_f32_e32 v78, v90
	v_exp_f32_e32 v79, v91
	v_mfma_f32_32x32x16_bf16 v[32:47], v[220:223], v[72:75], v[32:47]
	v_cvt_pk_bf16_f32 v76, v76, v77
	v_cvt_pk_bf16_f32 v77, v78, v79
	v_exp_f32_e32 v80, v92
	v_exp_f32_e32 v81, v93
	v_exp_f32_e32 v82, v94
	v_mfma_f32_32x32x16_bf16 v[0:15], v[232:235], v[72:75], v[0:15]
	v_exp_f32_e32 v83, v95
	v_cvt_pk_bf16_f32 v78, v80, v81
	v_cvt_pk_bf16_f32 v79, v82, v83
	s_nop 0
	s_nop 0
	v_mfma_f32_32x32x16_bf16 v[48:63], v[224:227], v[76:79], v[48:63]
	v_mfma_f32_32x32x16_bf16 v[32:47], v[228:231], v[76:79], v[32:47]
	v_mfma_f32_32x32x16_bf16 v[0:15], v[232:235], v[76:79], v[0:15]
	s_setprio 0
	s_andn2_b64 vcc, exec, s[8:9]
	s_cbranch_vccz .LBB0_451

; DI float xmax32(float x) { auto t = __builtin_amdgcn_permlane32_swap(__float_as_uint(x), __float_as_uint(x), false, false); return fmaxf(__uint_as_float(t[0]), __uint_as_float(t[1])); }
; template <int DK, int DV>
; DI void attn_map(f32x16 (&O)[DV / 32], float& lsum, const u16* qrow, const u16* K1, int ldk1, const u16* K2, int ldk2, const u16* Vt, int nkeys, char* smem) {
;     ...
;     float mx0 = fmaxf(fmaxf(s[0][0], s[0][1]), s[0][2]), mx1 = fmaxf(fmaxf(s[1][0], s[1][1]), s[1][2]);
; #pragma unroll
;     for (int i = 3; i < 15; i += 2) { mx0 = fmaxf(fmaxf(mx0, s[0][i]), s[0][i + 1]); mx1 = fmaxf(fmaxf(mx1, s[1][i]), s[1][i + 1]); }
;     float mx = fmaxf(fmaxf(mx0, mx1), fmaxf(s[0][15], s[1][15]));
;     mx = xmax32(mx);
;     const bool first = (k0 == 0);
;     if (first || __any(mx > 6.f)) {
;       float dl = first ? mx : fmaxf(mx, 0.f);
;       float alpha = __builtin_amdgcn_exp2f(-dl);
; #pragma unroll
;       for (int i = 0; i < 16; ++i) { negm[i] -= dl; lacc[i] *= alpha; }
; #pragma unroll
;       for (int dd = 0; dd < DV / 32; ++dd)
; #pragma unroll
;         for (int i = 0; i < 16; ++i) O[dd][i] *= alpha;
; #pragma unroll
;       for (int j = 0; j < 2; ++j)
; #pragma unroll
;         for (int i = 0; i < 16; ++i) s[j][i] -= dl;
;     }
.Lqk_join_D:
	s_nop 0
	v_max3_f32 v144, v64, v65, v66
	s_mov_b64 s[10:11], 0x4000
	v_lshl_add_u64 v[130:131], v[130:131], 0, s[56:57]
	v_lshl_add_u64 v[132:133], v[132:133], 0, s[56:57]
	v_lshl_add_u64 v[134:135], v[134:135], 0, s[10:11]
	v_lshl_add_u64 v[136:137], v[136:137], 0, s[10:11]
	v_mov_b64_e32 v[232:233], s[48:49]
	v_mov_b64_e32 v[234:235], s[50:51]
	s_nop 1
	v_max3_f32 v145, v80, v81, v82
	v_max3_f32 v144, v144, v67, v68
	v_max3_f32 v145, v145, v83, v84
	v_max3_f32 v144, v144, v69, v70
	v_max3_f32 v145, v145, v85, v86
	v_max3_f32 v144, v144, v71, v72
	v_max3_f32 v145, v145, v87, v88
	v_max3_f32 v144, v144, v73, v74
	v_max3_f32 v145, v145, v89, v90
	v_max3_f32 v144, v144, v75, v76
	v_max3_f32 v145, v145, v91, v92
	v_max_f32_e32 v146, v95, v95
	v_max_f32_e32 v147, v79, v79
	v_max3_f32 v144, v144, v77, v78
	v_max3_f32 v145, v145, v93, v94
	v_max_f32_e32 v146, v147, v146
	v_max3_f32 v144, v144, v145, v146
	v_mov_b32_e32 v145, v144
	s_nop 1
	v_permlane32_swap_b32_e32 v144, v145
	v_max_f32_e32 v145, v145, v145
	v_max_f32_e32 v144, v144, v144
	v_max_f32_e32 v144, v144, v145
	v_cmp_lt_f32_e32 vcc, s45, v144
	s_cbranch_vccz .LBB0_446
	v_max_f32_e32 v144, v144, v144
	v_max_f32_e32 v145, 0, v144
	v_exp_f32_e64 v144, -v145
	v_sub_f32_e32 v31, v31, v145
	v_sub_f32_e32 v30, v30, v145
	v_sub_f32_e32 v29, v29, v145
	v_pk_mul_f32 v[62:63], v[62:63], v[144:145] op_sel_hi:[1,0]
	v_pk_mul_f32 v[60:61], v[60:61], v[144:145] op_sel_hi:[1,0]
	v_pk_mul_f32 v[58:59], v[58:59], v[144:145] op_sel_hi:[1,0]
	v_pk_mul_f32 v[56:57], v[56:57], v[144:145] op_sel_hi:[1,0]
	v_pk_mul_f32 v[54:55], v[54:55], v[144:145] op_sel_hi:[1,0]
	v_pk_mul_f32 v[52:53], v[52:53], v[144:145] op_sel_hi:[1,0]
	v_pk_mul_f32 v[50:51], v[50:51], v[144:145] op_sel_hi:[1,0]
	v_pk_mul_f32 v[48:49], v[48:49], v[144:145] op_sel_hi:[1,0]
	v_pk_mul_f32 v[46:47], v[46:47], v[144:145] op_sel_hi:[1,0]
	v_pk_mul_f32 v[44:45], v[44:45], v[144:145] op_sel_hi:[1,0]
	v_pk_mul_f32 v[42:43], v[42:43], v[144:145] op_sel_hi:[1,0]
	v_pk_mul_f32 v[40:41], v[40:41], v[144:145] op_sel_hi:[1,0]
	v_pk_mul_f32 v[38:39], v[38:39], v[144:145] op_sel_hi:[1,0]
	v_pk_mul_f32 v[36:37], v[36:37], v[144:145] op_sel_hi:[1,0]
	v_pk_mul_f32 v[34:35], v[34:35], v[144:145] op_sel_hi:[1,0]
	v_pk_mul_f32 v[32:33], v[32:33], v[144:145] op_sel_hi:[1,0]
	v_sub_f32_e32 v28, v28, v145
	v_sub_f32_e32 v27, v27, v145
	v_sub_f32_e32 v26, v26, v145
	v_sub_f32_e32 v25, v25, v145
	v_sub_f32_e32 v24, v24, v145
	v_sub_f32_e32 v23, v23, v145
	v_sub_f32_e32 v22, v22, v145
	v_sub_f32_e32 v21, v21, v145
	v_sub_f32_e32 v20, v20, v145
	v_sub_f32_e32 v19, v19, v145
	v_sub_f32_e32 v18, v18, v145
	v_sub_f32_e32 v17, v17, v145
	v_sub_f32_e32 v16, v16, v145
	v_sub_f32_e32 v64, v64, v145
	v_sub_f32_e32 v65, v65, v145
	v_sub_f32_e32 v66, v66, v145
	v_sub_f32_e32 v67, v67, v145
	v_sub_f32_e32 v68, v68, v145
	v_sub_f32_e32 v69, v69, v145
	v_sub_f32_e32 v70, v70, v145
	v_sub_f32_e32 v71, v71, v145
	v_sub_f32_e32 v72, v72, v145
	v_sub_f32_e32 v73, v73, v145
	v_sub_f32_e32 v74, v74, v145
	v_sub_f32_e32 v75, v75, v145
	v_sub_f32_e32 v76, v76, v145
	v_sub_f32_e32 v77, v77, v145
	v_sub_f32_e32 v78, v78, v145
	v_sub_f32_e32 v79, v79, v145
	v_sub_f32_e32 v80, v80, v145
	v_sub_f32_e32 v81, v81, v145
	v_sub_f32_e32 v82, v82, v145
	v_sub_f32_e32 v83, v83, v145
	v_sub_f32_e32 v84, v84, v145
	v_sub_f32_e32 v85, v85, v145
	v_sub_f32_e32 v86, v86, v145
	v_sub_f32_e32 v87, v87, v145
	v_sub_f32_e32 v88, v88, v145
	v_sub_f32_e32 v89, v89, v145
	v_sub_f32_e32 v90, v90, v145
	v_sub_f32_e32 v91, v91, v145
	v_sub_f32_e32 v92, v92, v145
	v_sub_f32_e32 v93, v93, v145
	v_sub_f32_e32 v94, v94, v145
	v_sub_f32_e32 v95, v95, v145
	v_pk_mul_f32 v[14:15], v[14:15], v[144:145] op_sel_hi:[1,0]
	v_pk_mul_f32 v[12:13], v[12:13], v[144:145] op_sel_hi:[1,0]
	v_pk_mul_f32 v[10:11], v[10:11], v[144:145] op_sel_hi:[1,0]
	v_pk_mul_f32 v[8:9], v[8:9], v[144:145] op_sel_hi:[1,0]
	v_pk_mul_f32 v[6:7], v[6:7], v[144:145] op_sel_hi:[1,0]
	v_pk_mul_f32 v[4:5], v[4:5], v[144:145] op_sel_hi:[1,0]
	v_pk_mul_f32 v[2:3], v[2:3], v[144:145] op_sel_hi:[1,0]
	v_pk_mul_f32 v[0:1], v[0:1], v[144:145] op_sel_hi:[1,0]
	s_branch .LBB0_446
